# attention: PV MFMAs of the first sub-tile start three ops earlier inside the second sub-tile's softmax stream (first at op 11)
# baseline (speedup 1.0000x reference)
.Lat_nr1:
	v_exp_f32_e32 v64, v64
	v_exp_f32_e32 v65, v65
	v_exp_f32_e32 v66, v66
	v_exp_f32_e32 v67, v67
	v_add_f32_e32 v202, v202, v64
	v_exp_f32_e32 v68, v68
	v_exp_f32_e32 v69, v69
	v_add_f32_e32 v202, v202, v66
	v_exp_f32_e32 v70, v70
	v_add_f32_e32 v214, v65, v67
	v_cvt_pk_bf16_f32 v64, v64, v65
	v_exp_f32_e32 v71, v71
	v_add_f32_e32 v202, v202, v68
	v_exp_f32_e32 v72, v72
	v_add_f32_e32 v214, v214, v69
	v_cvt_pk_bf16_f32 v65, v66, v67
	v_exp_f32_e32 v73, v73
	v_add_f32_e32 v202, v202, v70
	v_exp_f32_e32 v74, v74
	v_add_f32_e32 v214, v214, v71
	v_cvt_pk_bf16_f32 v66, v68, v69
	v_exp_f32_e32 v75, v75
	v_add_f32_e32 v202, v202, v72
	v_exp_f32_e32 v76, v76
	v_add_f32_e32 v214, v214, v73
	v_cvt_pk_bf16_f32 v67, v70, v71
	v_exp_f32_e32 v77, v77
	v_add_f32_e32 v202, v202, v74
	s_waitcnt lgkmcnt(3)
	v_mfma_f32_32x32x16_bf16 v[16:31], v[236:239], v[64:67], v[16:31]
	v_exp_f32_e32 v78, v78
	v_add_f32_e32 v214, v214, v75
	v_cvt_pk_bf16_f32 v68, v72, v73
	v_exp_f32_e32 v79, v79
	v_add_f32_e32 v202, v202, v76
	v_exp_f32_e32 v80, v80
	v_add_f32_e32 v214, v214, v77
	v_cvt_pk_bf16_f32 v69, v74, v75
	s_waitcnt lgkmcnt(2)
	v_mfma_f32_32x32x16_bf16 v[0:15], v[240:243], v[64:67], v[0:15]
	v_exp_f32_e32 v81, v81
	v_add_f32_e32 v202, v202, v78
	v_exp_f32_e32 v82, v82
	v_add_f32_e32 v214, v214, v79
	v_cvt_pk_bf16_f32 v70, v76, v77
	v_exp_f32_e32 v83, v83
	v_add_f32_e32 v202, v202, v80
	v_exp_f32_e32 v84, v84
	v_add_f32_e32 v214, v214, v81
	v_cvt_pk_bf16_f32 v71, v78, v79
	v_exp_f32_e32 v85, v85
	v_add_f32_e32 v202, v202, v82
	s_waitcnt lgkmcnt(1)
	v_mfma_f32_32x32x16_bf16 v[16:31], v[244:247], v[68:71], v[16:31]
	v_exp_f32_e32 v86, v86
	v_add_f32_e32 v214, v214, v83
	v_cvt_pk_bf16_f32 v72, v80, v81
	v_exp_f32_e32 v87, v87
	v_add_f32_e32 v202, v202, v84
	v_exp_f32_e32 v88, v88
	v_add_f32_e32 v214, v214, v85
	v_cvt_pk_bf16_f32 v73, v82, v83
	s_waitcnt lgkmcnt(0)
	v_mfma_f32_32x32x16_bf16 v[0:15], v[248:251], v[68:71], v[0:15]
	v_exp_f32_e32 v89, v89
	v_add_f32_e32 v202, v202, v86
	v_exp_f32_e32 v90, v90
	v_add_f32_e32 v214, v214, v87
	v_cvt_pk_bf16_f32 v74, v84, v85
	v_exp_f32_e32 v91, v91
	v_add_f32_e32 v202, v202, v88
	v_exp_f32_e32 v92, v92
	v_add_f32_e32 v214, v214, v89
	v_cvt_pk_bf16_f32 v75, v86, v87
	v_exp_f32_e32 v93, v93
	v_add_f32_e32 v202, v202, v90
	v_exp_f32_e32 v94, v94
	v_add_f32_e32 v214, v214, v91
	v_cvt_pk_bf16_f32 v76, v88, v89
	v_exp_f32_e32 v95, v95
	v_add_f32_e32 v202, v202, v92
	v_add_f32_e32 v214, v214, v93
	v_cvt_pk_bf16_f32 v77, v90, v91
	v_add_f32_e32 v202, v202, v94
	v_add_f32_e32 v214, v214, v95
	v_cvt_pk_bf16_f32 v78, v92, v93
	v_cvt_pk_bf16_f32 v79, v94, v95
	v_add_f32_e32 v202, v202, v214
	ds_read_b128 v[80:83], v218 offset:13376
	ds_read_b128 v[84:87], v218 offset:17984
	ds_read_b128 v[88:91], v218 offset:13408
	ds_read_b128 v[92:95], v218 offset:18016
	v_exp_f32_e32 v96, v96
	v_exp_f32_e32 v97, v97
	v_exp_f32_e32 v98, v98
	v_exp_f32_e32 v99, v99
	v_add_f32_e32 v203, v203, v96
	v_exp_f32_e32 v100, v100
	v_exp_f32_e32 v101, v101
	v_add_f32_e32 v203, v203, v98
	v_exp_f32_e32 v102, v102
	v_add_f32_e32 v216, v97, v99
	v_cvt_pk_bf16_f32 v96, v96, v97
	s_waitcnt lgkmcnt(3)
	v_mfma_f32_32x32x16_bf16 v[16:31], v[80:83], v[72:75], v[16:31]
	v_exp_f32_e32 v103, v103
	v_add_f32_e32 v203, v203, v100
	v_exp_f32_e32 v104, v104
	v_add_f32_e32 v216, v216, v101
	v_cvt_pk_bf16_f32 v97, v98, v99
	v_exp_f32_e32 v105, v105
	v_add_f32_e32 v203, v203, v102
	v_exp_f32_e32 v106, v106
	s_waitcnt lgkmcnt(2)
	v_mfma_f32_32x32x16_bf16 v[0:15], v[84:87], v[72:75], v[0:15]
	v_add_f32_e32 v216, v216, v103
	v_cvt_pk_bf16_f32 v98, v100, v101
	v_exp_f32_e32 v107, v107
	v_add_f32_e32 v203, v203, v104
	v_exp_f32_e32 v108, v108
	v_add_f32_e32 v216, v216, v105
	v_cvt_pk_bf16_f32 v99, v102, v103
	v_exp_f32_e32 v109, v109
	s_waitcnt lgkmcnt(1)
	v_mfma_f32_32x32x16_bf16 v[16:31], v[88:91], v[76:79], v[16:31]
	v_add_f32_e32 v203, v203, v106
	v_exp_f32_e32 v110, v110
	v_add_f32_e32 v216, v216, v107
	v_cvt_pk_bf16_f32 v100, v104, v105
	v_exp_f32_e32 v111, v111
	v_add_f32_e32 v203, v203, v108
	v_exp_f32_e32 v112, v112
	v_add_f32_e32 v216, v216, v109
	s_waitcnt lgkmcnt(0)
	v_mfma_f32_32x32x16_bf16 v[0:15], v[92:95], v[76:79], v[0:15]
	v_cvt_pk_bf16_f32 v101, v106, v107
	v_exp_f32_e32 v113, v113
	v_add_f32_e32 v203, v203, v110
	v_exp_f32_e32 v114, v114
	v_add_f32_e32 v216, v216, v111
	v_cvt_pk_bf16_f32 v102, v108, v109
	v_exp_f32_e32 v115, v115
	v_add_f32_e32 v203, v203, v112
	v_mfma_f32_32x32x16_bf16 v[48:63], v[236:239], v[96:99], v[48:63]
	v_exp_f32_e32 v116, v116
	v_add_f32_e32 v216, v216, v113
	v_cvt_pk_bf16_f32 v103, v110, v111
	v_exp_f32_e32 v117, v117
	v_add_f32_e32 v203, v203, v114
	v_exp_f32_e32 v118, v118
	v_add_f32_e32 v216, v216, v115
	v_cvt_pk_bf16_f32 v104, v112, v113
	v_mfma_f32_32x32x16_bf16 v[32:47], v[240:243], v[96:99], v[32:47]
	v_exp_f32_e32 v119, v119
	v_add_f32_e32 v203, v203, v116
	v_exp_f32_e32 v120, v120
	v_add_f32_e32 v216, v216, v117
	v_cvt_pk_bf16_f32 v105, v114, v115
	v_exp_f32_e32 v121, v121
	v_add_f32_e32 v203, v203, v118
	v_exp_f32_e32 v122, v122
	v_mfma_f32_32x32x16_bf16 v[48:63], v[244:247], v[100:103], v[48:63]
	v_add_f32_e32 v216, v216, v119
	v_cvt_pk_bf16_f32 v106, v116, v117
	v_exp_f32_e32 v123, v123
	v_add_f32_e32 v203, v203, v120
	v_exp_f32_e32 v124, v124
	v_add_f32_e32 v216, v216, v121
	v_cvt_pk_bf16_f32 v107, v118, v119
	v_exp_f32_e32 v125, v125
	v_mfma_f32_32x32x16_bf16 v[32:47], v[248:251], v[100:103], v[32:47]
	v_add_f32_e32 v203, v203, v122
	v_exp_f32_e32 v126, v126
	v_add_f32_e32 v216, v216, v123
	v_cvt_pk_bf16_f32 v108, v120, v121
	v_exp_f32_e32 v127, v127
	v_add_f32_e32 v203, v203, v124
	v_add_f32_e32 v216, v216, v125
	v_cvt_pk_bf16_f32 v109, v122, v123
	v_add_f32_e32 v203, v203, v126
	v_add_f32_e32 v216, v216, v127
	v_cvt_pk_bf16_f32 v110, v124, v125
	v_cvt_pk_bf16_f32 v111, v126, v127
	v_add_f32_e32 v203, v203, v216
	s_nop 0
	v_mfma_f32_32x32x16_bf16 v[48:63], v[80:83], v[104:107], v[48:63]
	v_mfma_f32_32x32x16_bf16 v[32:47], v[84:87], v[104:107], v[32:47]
	v_mfma_f32_32x32x16_bf16 v[48:63], v[88:91], v[108:111], v[48:63]
	v_mfma_f32_32x32x16_bf16 v[32:47], v[92:95], v[108:111], v[32:47]
	s_cmp_eq_u32 s1, 64
	s_cbranch_scc1 .Lat_nowr
	s_cmp_eq_u32 s4, 1
	s_cselect_b32 s4, 0x5800, 0
	v_add3_u32 v214, s4, v225, v226
	v_add3_u32 v215, s4, v227, v228
	v_add3_u32 v216, s4, v229, v230
	v_add3_u32 v217, s4, v231, v200
	v_add3_u32 v196, s4, v232, v200
	s_waitcnt vmcnt(4)
	ds_write_b128 v214, v[176:179]
	s_waitcnt vmcnt(3)
	ds_write_b128 v215, v[180:183]
	s_waitcnt vmcnt(2)
	ds_write_b128 v216, v[184:187]
	s_waitcnt vmcnt(1)
	ds_write_b128 v217, v[188:191] offset:13312
	s_waitcnt vmcnt(0)
	ds_write_b128 v196, v[192:195] offset:13312
